# flat arrive/wait barrier before phases 6 and 14: affinities written through, conversion workgroups arrive and proceed, top-k workgroups wait on the counter; other router outputs released by the next f
# speedup vs baseline: 1.0046x; 1.0046x over previous
.LBB0_648:
	s_waitcnt vmcnt(0) lgkmcnt(0)
	s_barrier
	s_mov_b64 s[0:1], exec
	v_readlane_b32 s4, v197, 0
	v_readlane_b32 s5, v197, 1
	s_and_b64 s[4:5], s[0:1], s[4:5]
	s_mov_b64 exec, s[4:5]
	s_cbranch_execz .Lfb_a_0
	v_mov_b32_e32 v251, 0
	v_mov_b32_e32 v252, 1
	global_atomic_add v251, v252, s[92:93] offset:164
.Lfb_a_0:
	s_mov_b64 exec, s[0:1]
	s_cmp_gt_i32 s47, 63
	s_cbranch_scc1 .LBB0_700
	v_readlane_b32 s4, v197, 0
	v_readlane_b32 s5, v197, 1
	s_and_b64 s[4:5], s[0:1], s[4:5]
	s_mov_b64 exec, s[4:5]
	s_cbranch_execz .Lfb_w_0
	v_mov_b32_e32 v1, 0
.Lfb_spin_0:
	global_load_dword v2, v1, s[92:93] offset:164 sc1
	s_waitcnt vmcnt(0)
	v_cmp_le_u32_e32 vcc, s46, v2
	s_cbranch_vccnz .Lfb_out_0
	s_sleep 1
	s_branch .Lfb_spin_0

.Lfb_w_0:
	s_mov_b64 exec, s[0:1]
	s_branch .LBB0_700
	s_waitcnt vmcnt(0)
	s_waitcnt vmcnt(0) lgkmcnt(0)
	s_barrier
	s_mov_b64 s[0:1], exec
	v_readlane_b32 s4, v197, 0
	v_readlane_b32 s5, v197, 1
	s_and_b64 s[4:5], s[0:1], s[4:5]
	s_mov_b64 exec, s[4:5]
	s_cbranch_execz .LBB0_700
	s_add_i32 s4, 0, 0x24010
	v_mov_b32_e32 v1, s4
	s_waitcnt vmcnt(0) expcnt(0) lgkmcnt(0)
	ds_read_b32 v3, v1
	s_add_i32 s4, 0, 0x24014
	v_mov_b32_e32 v1, s4
	ds_read_b32 v1, v1
	s_waitcnt lgkmcnt(1)
	v_cmp_ne_u32_e32 vcc, 0, v3
	s_cbranch_vccnz .LBB0_664
	v_readlane_b32 s4, v196, 3
	v_readlane_b32 s5, v196, 4
	s_load_dwordx2 s[8:9], s[4:5], 0x4
	s_add_u32 s4, s92, 0x1000
	s_addc_u32 s5, s93, 0
	s_add_u32 s6, s92, 0x1100
	s_addc_u32 s7, s93, 0
	s_waitcnt lgkmcnt(0)
	s_mul_i32 s18, s8, s46
	s_add_u32 s8, s92, 0x1200
	s_mul_i32 s18, s18, s9
	s_addc_u32 s9, s93, 0
	s_add_u32 s10, s92, 0x1300
	s_addc_u32 s11, s93, 0
	s_mov_b32 s19, 1
	v_mov_b32_e32 v17, 0
	s_branch .LBB0_652

.LBB0_1237:
	s_waitcnt vmcnt(0) lgkmcnt(0)
	s_barrier
	s_mov_b64 s[0:1], exec
	v_readlane_b32 s2, v197, 0
	v_readlane_b32 s3, v197, 1
	s_and_b64 s[2:3], s[0:1], s[2:3]
	s_mov_b64 exec, s[2:3]
	s_cbranch_execz .Lfb_a_1
	v_mov_b32_e32 v251, 0
	v_mov_b32_e32 v252, 1
	global_atomic_add v251, v252, s[92:93] offset:168
.Lfb_a_1:
	s_mov_b64 exec, s[0:1]
	s_cmp_gt_i32 s47, 63
	s_cbranch_scc1 .LBB0_1289
	v_readlane_b32 s2, v197, 0
	v_readlane_b32 s3, v197, 1
	s_and_b64 s[2:3], s[0:1], s[2:3]
	s_mov_b64 exec, s[2:3]
	s_cbranch_execz .Lfb_w_1
	v_mov_b32_e32 v1, 0
.Lfb_spin_1:
	global_load_dword v2, v1, s[92:93] offset:168 sc1
	s_waitcnt vmcnt(0)
	v_cmp_le_u32_e32 vcc, s46, v2
	s_cbranch_vccnz .Lfb_out_1
	s_sleep 1
	s_branch .Lfb_spin_1

.Lfb_w_1:
	s_mov_b64 exec, s[0:1]
	s_branch .LBB0_1289
	s_waitcnt vmcnt(0)
	s_waitcnt vmcnt(0) lgkmcnt(0)
	s_barrier
	s_mov_b64 s[0:1], exec
	v_readlane_b32 s2, v197, 0
	v_readlane_b32 s3, v197, 1
	s_and_b64 s[2:3], s[0:1], s[2:3]
	s_mov_b64 exec, s[2:3]
	s_cbranch_execz .LBB0_1289
	s_add_i32 s2, 0, 0x24010
	v_mov_b32_e32 v1, s2
	s_waitcnt vmcnt(0) expcnt(0) lgkmcnt(0)
	ds_read_b32 v3, v1
	s_add_i32 s2, 0, 0x24014
	v_mov_b32_e32 v1, s2
	ds_read_b32 v1, v1
	s_waitcnt lgkmcnt(1)
	v_cmp_ne_u32_e32 vcc, 0, v3
	s_cbranch_vccnz .LBB0_1253
	v_readlane_b32 s2, v196, 3
	v_readlane_b32 s3, v196, 4
	s_load_dwordx2 s[6:7], s[2:3], 0x4
	s_add_u32 s2, s92, 0x1000
	s_addc_u32 s3, s93, 0
	s_add_u32 s4, s92, 0x1100
	s_addc_u32 s5, s93, 0
	s_waitcnt lgkmcnt(0)
	s_mul_i32 s16, s6, s46
	s_add_u32 s6, s92, 0x1200
	s_mul_i32 s16, s16, s7
	s_addc_u32 s7, s93, 0
	s_add_u32 s8, s92, 0x1300
	s_addc_u32 s9, s93, 0
	s_mov_b32 s17, 1
	v_mov_b32_e32 v17, 0
	s_branch .LBB0_1241
